# grid-barrier L1 invalidate hoisted above the release spin; EpiUp scale/conv-weight loads issued together above its barrier
# speedup vs baseline: 1.0605x; 1.0092x over previous
; __device__ __forceinline__ unsigned xb_ld(unsigned* p)              { return __hip_atomic_load(p, __ATOMIC_RELAXED, __HIP_MEMORY_SCOPE_AGENT); }
; __device__ __forceinline__ unsigned xb_add(unsigned* p, unsigned v) { return __hip_atomic_fetch_add(p, v, __ATOMIC_RELAXED, __HIP_MEMORY_SCOPE_AGENT); }
; #define XB_SPIN(cond, bar) do { unsigned _sp = 0; while (cond) { \
;     if ((++_sp & 255u) == 0u) { if (xb_ld(&(bar)[XB_TMO])) break; if (_sp > XB_SPIN_CAP) { atomicAdd(&(bar)[XB_TMO], 1u); break; } } } } while (0)
; __device__ __forceinline__ void xcd_barrier(const XcdBarrier& b) {
;     ...
;         const unsigned old = xb_add(&bar[XB_XSUB(b.x)], 1u);
;         const unsigned gen = old / nloc;
;         if (old + 1u == (gen + 1u) * nloc) {
;             __builtin_amdgcn_fence(__ATOMIC_RELEASE, "agent");
;             asm volatile("s_waitcnt vmcnt(0)" ::: "memory");
;             const unsigned og = xb_add(&bar[XB_TOP], 1u);
;             const unsigned tg = og / nx;
;             if (og + 1u == (tg + 1u) * nx) xb_add(&bar[XB_TOPGEN], 1u);
;             else XB_SPIN(xb_ld(&bar[XB_TOPGEN]) == tg, bar);
;             __builtin_amdgcn_fence(__ATOMIC_ACQUIRE, "agent");
;             xb_add(&bar[XB_XGEN(b.x)], 1u);
;             asm volatile("s_waitcnt vmcnt(0)" ::: "memory");
;         } else {
;             XB_SPIN(xb_ld(&bar[XB_XGEN(b.x)]) == gen, bar);
.LBB0_191:
	s_or_b64 exec, exec, s[8:9]
	v_cvt_f32_u32_e32 v4, v2
	s_waitcnt vmcnt(0)
	v_readfirstlane_b32 s6, v3
	v_sub_u32_e32 v3, 0, v2
	v_rcp_iflag_f32_e32 v4, v4
	v_add_u32_e32 v5, s6, v1
	v_mul_f32_e32 v4, 0x4f7ffffe, v4
	v_cvt_u32_f32_e32 v4, v4
	v_mul_lo_u32 v1, v3, v4
	v_mul_hi_u32 v1, v4, v1
	v_add_u32_e32 v1, v4, v1
	v_mul_hi_u32 v1, v5, v1
	v_mul_lo_u32 v3, v1, v2
	v_sub_u32_e32 v3, v5, v3
	v_add_u32_e32 v4, 1, v1
	v_cmp_ge_u32_e32 vcc, v3, v2
	s_nop 1
	v_cndmask_b32_e32 v1, v1, v4, vcc
	v_sub_u32_e32 v4, v3, v2
	v_cndmask_b32_e32 v3, v3, v4, vcc
	v_add_u32_e32 v4, 1, v1
	v_cmp_ge_u32_e32 vcc, v3, v2
	v_add_u32_e32 v3, 1, v5
	s_nop 0
	v_cndmask_b32_e32 v1, v1, v4, vcc
	v_mul_lo_u32 v4, v2, v1
	v_add_u32_e32 v2, v4, v2
	v_cmp_ne_u32_e32 vcc, v3, v2
	s_and_saveexec_b64 s[6:7], vcc
	s_xor_b64 s[6:7], exec, s[6:7]
	s_cbranch_execz .LBB0_205
	buffer_inv sc1
	s_waitcnt lgkmcnt(0)
	v_mov_b32_e32 v0, 0x2000
	global_load_dword v0, v0, s[4:5] offset:1024 sc1
	s_add_u32 s12, s4, 0x2400
	s_addc_u32 s13, s5, 0
	s_waitcnt vmcnt(0)
	v_cmp_eq_u32_e32 vcc, v0, v1
	s_and_saveexec_b64 s[8:9], vcc
	s_cbranch_execz .LBB0_204
	s_add_u32 s10, s0, 0x221e4200
	s_addc_u32 s11, s1, 0
	s_mov_b32 s24, 1
	s_mov_b64 s[14:15], 0
	v_mov_b32_e32 v0, 0
	s_branch .LBB0_195

; __device__ __forceinline__ unsigned xb_ld(unsigned* p)              { return __hip_atomic_load(p, __ATOMIC_RELAXED, __HIP_MEMORY_SCOPE_AGENT); }
; __device__ __forceinline__ unsigned xb_add(unsigned* p, unsigned v) { return __hip_atomic_fetch_add(p, v, __ATOMIC_RELAXED, __HIP_MEMORY_SCOPE_AGENT); }
; #define XB_SPIN(cond, bar) do { unsigned _sp = 0; while (cond) { \
;     if ((++_sp & 255u) == 0u) { if (xb_ld(&(bar)[XB_TMO])) break; if (_sp > XB_SPIN_CAP) { atomicAdd(&(bar)[XB_TMO], 1u); break; } } } } while (0)
; __device__ __forceinline__ void xcd_barrier(const XcdBarrier& b) {
;     ...
;             __builtin_amdgcn_fence(__ATOMIC_RELEASE, "agent");
;             asm volatile("s_waitcnt vmcnt(0)" ::: "memory");
;             const unsigned og = xb_add(&bar[XB_TOP], 1u);
;             const unsigned tg = og / nx;
;             if (og + 1u == (tg + 1u) * nx) xb_add(&bar[XB_TOPGEN], 1u);
;             else XB_SPIN(xb_ld(&bar[XB_TOPGEN]) == tg, bar);
;             __builtin_amdgcn_fence(__ATOMIC_ACQUIRE, "agent");
;             xb_add(&bar[XB_XGEN(b.x)], 1u);
;             asm volatile("s_waitcnt vmcnt(0)" ::: "memory");
;         } else {
;             XB_SPIN(xb_ld(&bar[XB_XGEN(b.x)]) == gen, bar);
;             __builtin_amdgcn_fence(__ATOMIC_ACQUIRE, "agent");
;             asm volatile("s_waitcnt vmcnt(0)" ::: "memory");
.LBB0_204:
	s_or_b64 exec, exec, s[8:9]
	s_waitcnt vmcnt(0)
	s_waitcnt vmcnt(0)
.LBB0_205:
	s_andn2_saveexec_b64 s[6:7], s[6:7]
	s_cbranch_execz .LBB0_225
	s_mov_b64 s[6:7], exec
	buffer_wbl2 sc1
	s_waitcnt lgkmcnt(0)
	s_waitcnt vmcnt(0)
	buffer_inv sc1
	v_mbcnt_lo_u32_b32 v1, s6, 0
	v_mbcnt_hi_u32_b32 v1, s7, v1
	v_cmp_eq_u32_e32 vcc, 0, v1
	s_and_saveexec_b64 s[8:9], vcc
	s_cbranch_execz .LBB0_208
	s_bcnt1_i32_b64 s6, s[6:7]
	v_mov_b32_e32 v2, 0x221e7000
	v_mov_b32_e32 v3, s6
	global_atomic_add v2, v2, v3, s[0:1] offset:1024 sc0

; __device__ __forceinline__ unsigned xb_ld(unsigned* p)              { return __hip_atomic_load(p, __ATOMIC_RELAXED, __HIP_MEMORY_SCOPE_AGENT); }
; __device__ __forceinline__ unsigned xb_add(unsigned* p, unsigned v) { return __hip_atomic_fetch_add(p, v, __ATOMIC_RELAXED, __HIP_MEMORY_SCOPE_AGENT); }
; #define XB_SPIN(cond, bar) do { unsigned _sp = 0; while (cond) { \
;     if ((++_sp & 255u) == 0u) { if (xb_ld(&(bar)[XB_TMO])) break; if (_sp > XB_SPIN_CAP) { atomicAdd(&(bar)[XB_TMO], 1u); break; } } } } while (0)
; __device__ __forceinline__ void xcd_barrier(const XcdBarrier& b) {
;     ...
;             if (og + 1u == (tg + 1u) * nx) xb_add(&bar[XB_TOPGEN], 1u);
;             else XB_SPIN(xb_ld(&bar[XB_TOPGEN]) == tg, bar);
;             __builtin_amdgcn_fence(__ATOMIC_ACQUIRE, "agent");
;             xb_add(&bar[XB_XGEN(b.x)], 1u);
;             asm volatile("s_waitcnt vmcnt(0)" ::: "memory");
.LBB0_222:
	s_or_b64 exec, exec, s[6:7]
	s_mov_b64 s[6:7], exec
	v_mbcnt_lo_u32_b32 v0, s6, 0
	v_mbcnt_hi_u32_b32 v0, s7, v0
	v_cmp_eq_u32_e32 vcc, 0, v0
	s_waitcnt vmcnt(0)
	s_and_saveexec_b64 s[8:9], vcc
	s_cbranch_execz .LBB0_224
	s_bcnt1_i32_b64 s6, s[6:7]
	v_mov_b32_e32 v0, 0x2000
	v_mov_b32_e32 v1, s6
	global_atomic_add v0, v1, s[4:5] offset:1024

; __device__ __forceinline__ unsigned xb_ld(unsigned* p)              { return __hip_atomic_load(p, __ATOMIC_RELAXED, __HIP_MEMORY_SCOPE_AGENT); }
; __device__ __forceinline__ unsigned xb_add(unsigned* p, unsigned v) { return __hip_atomic_fetch_add(p, v, __ATOMIC_RELAXED, __HIP_MEMORY_SCOPE_AGENT); }
; #define XB_SPIN(cond, bar) do { unsigned _sp = 0; while (cond) { \
;     if ((++_sp & 255u) == 0u) { if (xb_ld(&(bar)[XB_TMO])) break; if (_sp > XB_SPIN_CAP) { atomicAdd(&(bar)[XB_TMO], 1u); break; } } } } while (0)
; __device__ __forceinline__ void xcd_barrier(const XcdBarrier& b) {
;     ...
;         const unsigned old = xb_add(&bar[XB_XSUB(b.x)], 1u);
;         const unsigned gen = old / nloc;
;         if (old + 1u == (gen + 1u) * nloc) {
;             __builtin_amdgcn_fence(__ATOMIC_RELEASE, "agent");
;             asm volatile("s_waitcnt vmcnt(0)" ::: "memory");
;             const unsigned og = xb_add(&bar[XB_TOP], 1u);
;             const unsigned tg = og / nx;
;             if (og + 1u == (tg + 1u) * nx) xb_add(&bar[XB_TOPGEN], 1u);
;             else XB_SPIN(xb_ld(&bar[XB_TOPGEN]) == tg, bar);
;             __builtin_amdgcn_fence(__ATOMIC_ACQUIRE, "agent");
;             xb_add(&bar[XB_XGEN(b.x)], 1u);
;             asm volatile("s_waitcnt vmcnt(0)" ::: "memory");
;         } else {
;             XB_SPIN(xb_ld(&bar[XB_XGEN(b.x)]) == gen, bar);
.LBB0_311:
	s_or_b64 exec, exec, s[2:3]
	v_cvt_f32_u32_e32 v4, v2
	s_waitcnt vmcnt(0)
	v_readfirstlane_b32 s2, v3
	v_sub_u32_e32 v3, 0, v2
	v_rcp_iflag_f32_e32 v4, v4
	v_add_u32_e32 v5, s2, v1
	v_mul_f32_e32 v4, 0x4f7ffffe, v4
	v_cvt_u32_f32_e32 v4, v4
	v_mul_lo_u32 v1, v3, v4
	v_mul_hi_u32 v1, v4, v1
	v_add_u32_e32 v1, v4, v1
	v_mul_hi_u32 v1, v5, v1
	v_mul_lo_u32 v3, v1, v2
	v_sub_u32_e32 v3, v5, v3
	v_add_u32_e32 v4, 1, v1
	v_sub_u32_e32 v6, v3, v2
	v_cmp_ge_u32_e32 vcc, v3, v2
	s_nop 1
	v_cndmask_b32_e32 v1, v1, v4, vcc
	v_cndmask_b32_e32 v3, v3, v6, vcc
	v_add_u32_e32 v4, 1, v1
	v_cmp_ge_u32_e32 vcc, v3, v2
	v_add_u32_e32 v3, 1, v5
	s_nop 0
	v_cndmask_b32_e32 v1, v1, v4, vcc
	v_mul_lo_u32 v4, v2, v1
	v_add_u32_e32 v2, v4, v2
	v_cmp_ne_u32_e32 vcc, v3, v2
	s_and_saveexec_b64 s[2:3], vcc
	s_xor_b64 s[2:3], exec, s[2:3]
	s_cbranch_execz .LBB0_325
	buffer_inv sc1
	v_readlane_b32 s6, v245, 13
	v_readlane_b32 s7, v245, 14
	s_waitcnt lgkmcnt(0)
	s_nop 3
	global_load_dword v0, v169, s[6:7] sc1
	s_waitcnt vmcnt(0)
	v_cmp_eq_u32_e32 vcc, v0, v1
	s_and_saveexec_b64 s[6:7], vcc
	s_cbranch_execz .LBB0_324
	s_mov_b32 s10, 1
	s_mov_b64 s[8:9], 0
	s_branch .LBB0_315

; __device__ __forceinline__ unsigned xb_ld(unsigned* p)              { return __hip_atomic_load(p, __ATOMIC_RELAXED, __HIP_MEMORY_SCOPE_AGENT); }
; __device__ __forceinline__ unsigned xb_add(unsigned* p, unsigned v) { return __hip_atomic_fetch_add(p, v, __ATOMIC_RELAXED, __HIP_MEMORY_SCOPE_AGENT); }
; #define XB_SPIN(cond, bar) do { unsigned _sp = 0; while (cond) { \
;     if ((++_sp & 255u) == 0u) { if (xb_ld(&(bar)[XB_TMO])) break; if (_sp > XB_SPIN_CAP) { atomicAdd(&(bar)[XB_TMO], 1u); break; } } } } while (0)
; __device__ __forceinline__ void xcd_barrier(const XcdBarrier& b) {
;     ...
;             __builtin_amdgcn_fence(__ATOMIC_RELEASE, "agent");
;             asm volatile("s_waitcnt vmcnt(0)" ::: "memory");
;             const unsigned og = xb_add(&bar[XB_TOP], 1u);
;             const unsigned tg = og / nx;
;             if (og + 1u == (tg + 1u) * nx) xb_add(&bar[XB_TOPGEN], 1u);
;             else XB_SPIN(xb_ld(&bar[XB_TOPGEN]) == tg, bar);
;             __builtin_amdgcn_fence(__ATOMIC_ACQUIRE, "agent");
;             xb_add(&bar[XB_XGEN(b.x)], 1u);
;             asm volatile("s_waitcnt vmcnt(0)" ::: "memory");
;         } else {
;             XB_SPIN(xb_ld(&bar[XB_XGEN(b.x)]) == gen, bar);
;             __builtin_amdgcn_fence(__ATOMIC_ACQUIRE, "agent");
;             asm volatile("s_waitcnt vmcnt(0)" ::: "memory");
.LBB0_324:
	s_or_b64 exec, exec, s[6:7]
	s_waitcnt vmcnt(0)
	s_waitcnt vmcnt(0)
.LBB0_325:
	s_andn2_saveexec_b64 s[2:3], s[2:3]
	s_cbranch_execz .LBB0_345
	s_mov_b64 s[6:7], exec
	buffer_wbl2 sc1
	s_waitcnt lgkmcnt(0)
	s_waitcnt vmcnt(0)
	buffer_inv sc1
	v_mbcnt_lo_u32_b32 v1, s6, 0
	v_mbcnt_hi_u32_b32 v1, s7, v1
	v_cmp_eq_u32_e32 vcc, 0, v1
	s_and_saveexec_b64 s[8:9], vcc
	s_cbranch_execz .LBB0_328
	s_bcnt1_i32_b64 s6, s[6:7]
	v_mov_b32_e32 v2, s6
	v_readlane_b32 s6, v245, 15
	v_readlane_b32 s7, v245, 16
	s_nop 4
	global_atomic_add v2, v169, v2, s[6:7] sc0

; __device__ __forceinline__ unsigned xb_ld(unsigned* p)              { return __hip_atomic_load(p, __ATOMIC_RELAXED, __HIP_MEMORY_SCOPE_AGENT); }
; __device__ __forceinline__ unsigned xb_add(unsigned* p, unsigned v) { return __hip_atomic_fetch_add(p, v, __ATOMIC_RELAXED, __HIP_MEMORY_SCOPE_AGENT); }
; #define XB_SPIN(cond, bar) do { unsigned _sp = 0; while (cond) { \
;     if ((++_sp & 255u) == 0u) { if (xb_ld(&(bar)[XB_TMO])) break; if (_sp > XB_SPIN_CAP) { atomicAdd(&(bar)[XB_TMO], 1u); break; } } } } while (0)
; __device__ __forceinline__ void xcd_barrier(const XcdBarrier& b) {
;     ...
;             if (og + 1u == (tg + 1u) * nx) xb_add(&bar[XB_TOPGEN], 1u);
;             else XB_SPIN(xb_ld(&bar[XB_TOPGEN]) == tg, bar);
;             __builtin_amdgcn_fence(__ATOMIC_ACQUIRE, "agent");
;             xb_add(&bar[XB_XGEN(b.x)], 1u);
;             asm volatile("s_waitcnt vmcnt(0)" ::: "memory");
.LBB0_342:
	s_or_b64 exec, exec, s[6:7]
	s_mov_b64 s[6:7], exec
	v_mbcnt_lo_u32_b32 v0, s6, 0
	v_mbcnt_hi_u32_b32 v0, s7, v0
	v_cmp_eq_u32_e32 vcc, 0, v0
	s_waitcnt vmcnt(0)
	s_and_saveexec_b64 s[8:9], vcc
	s_cbranch_execz .LBB0_344
	s_bcnt1_i32_b64 s6, s[6:7]
	v_mov_b32_e32 v0, s6
	v_readlane_b32 s6, v245, 13
	v_readlane_b32 s7, v245, 14
	s_nop 4
	global_atomic_add v169, v0, s[6:7]

; __device__ __forceinline__ unsigned xb_ld(unsigned* p)              { return __hip_atomic_load(p, __ATOMIC_RELAXED, __HIP_MEMORY_SCOPE_AGENT); }
; __device__ __forceinline__ unsigned xb_add(unsigned* p, unsigned v) { return __hip_atomic_fetch_add(p, v, __ATOMIC_RELAXED, __HIP_MEMORY_SCOPE_AGENT); }
; #define XB_SPIN(cond, bar) do { unsigned _sp = 0; while (cond) { \
;     if ((++_sp & 255u) == 0u) { if (xb_ld(&(bar)[XB_TMO])) break; if (_sp > XB_SPIN_CAP) { atomicAdd(&(bar)[XB_TMO], 1u); break; } } } } while (0)
; __device__ __forceinline__ void xcd_barrier(const XcdBarrier& b) {
;     ...
;         const unsigned old = xb_add(&bar[XB_XSUB(b.x)], 1u);
;         const unsigned gen = old / nloc;
;         if (old + 1u == (gen + 1u) * nloc) {
;             __builtin_amdgcn_fence(__ATOMIC_RELEASE, "agent");
;             asm volatile("s_waitcnt vmcnt(0)" ::: "memory");
;             const unsigned og = xb_add(&bar[XB_TOP], 1u);
;             const unsigned tg = og / nx;
;             if (og + 1u == (tg + 1u) * nx) xb_add(&bar[XB_TOPGEN], 1u);
;             else XB_SPIN(xb_ld(&bar[XB_TOPGEN]) == tg, bar);
;             __builtin_amdgcn_fence(__ATOMIC_ACQUIRE, "agent");
;             xb_add(&bar[XB_XGEN(b.x)], 1u);
;             asm volatile("s_waitcnt vmcnt(0)" ::: "memory");
;         } else {
;             XB_SPIN(xb_ld(&bar[XB_XGEN(b.x)]) == gen, bar);
.LBB0_394:
	s_or_b64 exec, exec, s[4:5]
	v_cvt_f32_u32_e32 v4, v2
	s_waitcnt vmcnt(0)
	v_readfirstlane_b32 s4, v3
	v_sub_u32_e32 v3, 0, v2
	v_rcp_iflag_f32_e32 v4, v4
	v_add_u32_e32 v5, s4, v1
	v_mul_f32_e32 v4, 0x4f7ffffe, v4
	v_cvt_u32_f32_e32 v4, v4
	v_mul_lo_u32 v1, v3, v4
	v_mul_hi_u32 v1, v4, v1
	v_add_u32_e32 v1, v4, v1
	v_mul_hi_u32 v1, v5, v1
	v_mul_lo_u32 v3, v1, v2
	v_sub_u32_e32 v3, v5, v3
	v_add_u32_e32 v4, 1, v1
	v_cmp_ge_u32_e32 vcc, v3, v2
	s_nop 1
	v_cndmask_b32_e32 v1, v1, v4, vcc
	v_sub_u32_e32 v4, v3, v2
	v_cndmask_b32_e32 v3, v3, v4, vcc
	v_add_u32_e32 v4, 1, v1
	v_cmp_ge_u32_e32 vcc, v3, v2
	v_add_u32_e32 v3, 1, v5
	s_nop 0
	v_cndmask_b32_e32 v1, v1, v4, vcc
	v_mul_lo_u32 v4, v2, v1
	v_add_u32_e32 v2, v4, v2
	v_cmp_ne_u32_e32 vcc, v3, v2
	s_and_saveexec_b64 s[4:5], vcc
	s_xor_b64 s[4:5], exec, s[4:5]
	s_cbranch_execz .LBB0_408
	buffer_inv sc1
	v_readlane_b32 s0, v245, 13
	v_readlane_b32 s1, v245, 14
	s_waitcnt lgkmcnt(0)
	s_nop 3
	global_load_dword v0, v169, s[0:1] sc1
	s_waitcnt vmcnt(0)
	v_cmp_eq_u32_e32 vcc, v0, v1
	s_and_saveexec_b64 s[6:7], vcc
	s_cbranch_execz .LBB0_407
	s_mov_b32 s10, 1
	s_mov_b64 s[8:9], 0
	s_branch .LBB0_398

; __device__ __forceinline__ unsigned xb_add(unsigned* p, unsigned v) { return __hip_atomic_fetch_add(p, v, __ATOMIC_RELAXED, __HIP_MEMORY_SCOPE_AGENT); }
; __device__ __forceinline__ void xcd_barrier(const XcdBarrier& b) {
;     ...
;             __builtin_amdgcn_fence(__ATOMIC_RELEASE, "agent");
;             asm volatile("s_waitcnt vmcnt(0)" ::: "memory");
;             const unsigned og = xb_add(&bar[XB_TOP], 1u);
.LBB0_408:
	s_andn2_saveexec_b64 s[4:5], s[4:5]
	s_cbranch_execz .LBB0_428
	s_mov_b64 s[4:5], exec
	buffer_wbl2 sc1
	s_waitcnt lgkmcnt(0)
	s_waitcnt vmcnt(0)
	buffer_inv sc1
	v_mbcnt_lo_u32_b32 v1, s4, 0
	v_mbcnt_hi_u32_b32 v1, s5, v1
	v_cmp_eq_u32_e32 vcc, 0, v1
	s_and_saveexec_b64 s[6:7], vcc
	s_cbranch_execz .LBB0_411
	s_bcnt1_i32_b64 s4, s[4:5]
	v_readlane_b32 s0, v245, 15
	v_mov_b32_e32 v2, s4
	v_readlane_b32 s1, v245, 16
	s_nop 4
	global_atomic_add v2, v169, v2, s[0:1] sc0

; __device__ __forceinline__ unsigned xb_ld(unsigned* p)              { return __hip_atomic_load(p, __ATOMIC_RELAXED, __HIP_MEMORY_SCOPE_AGENT); }
; __device__ __forceinline__ unsigned xb_add(unsigned* p, unsigned v) { return __hip_atomic_fetch_add(p, v, __ATOMIC_RELAXED, __HIP_MEMORY_SCOPE_AGENT); }
; #define XB_SPIN(cond, bar) do { unsigned _sp = 0; while (cond) { \
;     if ((++_sp & 255u) == 0u) { if (xb_ld(&(bar)[XB_TMO])) break; if (_sp > XB_SPIN_CAP) { atomicAdd(&(bar)[XB_TMO], 1u); break; } } } } while (0)
; __device__ __forceinline__ void xcd_barrier(const XcdBarrier& b) {
;     ...
;             if (og + 1u == (tg + 1u) * nx) xb_add(&bar[XB_TOPGEN], 1u);
;             else XB_SPIN(xb_ld(&bar[XB_TOPGEN]) == tg, bar);
;             __builtin_amdgcn_fence(__ATOMIC_ACQUIRE, "agent");
;             xb_add(&bar[XB_XGEN(b.x)], 1u);
;             asm volatile("s_waitcnt vmcnt(0)" ::: "memory");
.LBB0_425:
	s_or_b64 exec, exec, s[4:5]
	s_mov_b64 s[4:5], exec
	v_mbcnt_lo_u32_b32 v0, s4, 0
	v_mbcnt_hi_u32_b32 v0, s5, v0
	v_cmp_eq_u32_e32 vcc, 0, v0
	s_waitcnt vmcnt(0)
	s_and_saveexec_b64 s[6:7], vcc
	s_cbranch_execz .LBB0_427
	s_bcnt1_i32_b64 s4, s[4:5]
	v_readlane_b32 s0, v245, 13
	v_mov_b32_e32 v0, s4
	v_readlane_b32 s1, v245, 14
	s_nop 4
	global_atomic_add v169, v0, s[0:1]

; __device__ __forceinline__ unsigned xb_ld(unsigned* p)              { return __hip_atomic_load(p, __ATOMIC_RELAXED, __HIP_MEMORY_SCOPE_AGENT); }
; __device__ __forceinline__ unsigned xb_add(unsigned* p, unsigned v) { return __hip_atomic_fetch_add(p, v, __ATOMIC_RELAXED, __HIP_MEMORY_SCOPE_AGENT); }
; #define XB_SPIN(cond, bar) do { unsigned _sp = 0; while (cond) { \
;     if ((++_sp & 255u) == 0u) { if (xb_ld(&(bar)[XB_TMO])) break; if (_sp > XB_SPIN_CAP) { atomicAdd(&(bar)[XB_TMO], 1u); break; } } } } while (0)
; __device__ __forceinline__ void xcd_barrier(const XcdBarrier& b) {
;     ...
;         const unsigned old = xb_add(&bar[XB_XSUB(b.x)], 1u);
;         const unsigned gen = old / nloc;
;         if (old + 1u == (gen + 1u) * nloc) {
;             __builtin_amdgcn_fence(__ATOMIC_RELEASE, "agent");
;             asm volatile("s_waitcnt vmcnt(0)" ::: "memory");
;             const unsigned og = xb_add(&bar[XB_TOP], 1u);
;             const unsigned tg = og / nx;
;             if (og + 1u == (tg + 1u) * nx) xb_add(&bar[XB_TOPGEN], 1u);
;             else XB_SPIN(xb_ld(&bar[XB_TOPGEN]) == tg, bar);
;             __builtin_amdgcn_fence(__ATOMIC_ACQUIRE, "agent");
;             xb_add(&bar[XB_XGEN(b.x)], 1u);
;             asm volatile("s_waitcnt vmcnt(0)" ::: "memory");
;         } else {
;             XB_SPIN(xb_ld(&bar[XB_XGEN(b.x)]) == gen, bar);
.LBB0_451:
	s_or_b64 exec, exec, s[4:5]
	v_cvt_f32_u32_e32 v4, v2
	s_waitcnt vmcnt(0)
	v_readfirstlane_b32 s4, v3
	v_sub_u32_e32 v3, 0, v2
	v_rcp_iflag_f32_e32 v4, v4
	v_add_u32_e32 v5, s4, v1
	v_mul_f32_e32 v4, 0x4f7ffffe, v4
	v_cvt_u32_f32_e32 v4, v4
	v_mul_lo_u32 v1, v3, v4
	v_mul_hi_u32 v1, v4, v1
	v_add_u32_e32 v1, v4, v1
	v_mul_hi_u32 v1, v5, v1
	v_mul_lo_u32 v3, v1, v2
	v_sub_u32_e32 v3, v5, v3
	v_add_u32_e32 v4, 1, v1
	v_cmp_ge_u32_e32 vcc, v3, v2
	s_nop 1
	v_cndmask_b32_e32 v1, v1, v4, vcc
	v_sub_u32_e32 v4, v3, v2
	v_cndmask_b32_e32 v3, v3, v4, vcc
	v_add_u32_e32 v4, 1, v1
	v_cmp_ge_u32_e32 vcc, v3, v2
	v_add_u32_e32 v3, 1, v5
	s_nop 0
	v_cndmask_b32_e32 v1, v1, v4, vcc
	v_mul_lo_u32 v4, v2, v1
	v_add_u32_e32 v2, v4, v2
	v_cmp_ne_u32_e32 vcc, v3, v2
	s_and_saveexec_b64 s[4:5], vcc
	s_xor_b64 s[4:5], exec, s[4:5]
	s_cbranch_execz .LBB0_465
	buffer_inv sc1
	v_readlane_b32 s6, v245, 13
	v_readlane_b32 s7, v245, 14
	s_waitcnt lgkmcnt(0)
	s_nop 3
	global_load_dword v0, v169, s[6:7] sc1
	s_waitcnt vmcnt(0)
	v_cmp_eq_u32_e32 vcc, v0, v1
	s_and_saveexec_b64 s[6:7], vcc
	s_cbranch_execz .LBB0_464
	s_mov_b32 s10, 1
	s_mov_b64 s[8:9], 0
	s_branch .LBB0_455

; __device__ __forceinline__ unsigned xb_add(unsigned* p, unsigned v) { return __hip_atomic_fetch_add(p, v, __ATOMIC_RELAXED, __HIP_MEMORY_SCOPE_AGENT); }
; __device__ __forceinline__ void xcd_barrier(const XcdBarrier& b) {
;     ...
;             __builtin_amdgcn_fence(__ATOMIC_RELEASE, "agent");
;             asm volatile("s_waitcnt vmcnt(0)" ::: "memory");
;             const unsigned og = xb_add(&bar[XB_TOP], 1u);
.LBB0_465:
	s_andn2_saveexec_b64 s[4:5], s[4:5]
	s_cbranch_execz .LBB0_485
	s_mov_b64 s[4:5], exec
	buffer_wbl2 sc1
	s_waitcnt lgkmcnt(0)
	s_waitcnt vmcnt(0)
	buffer_inv sc1
	v_mbcnt_lo_u32_b32 v1, s4, 0
	v_mbcnt_hi_u32_b32 v1, s5, v1
	v_cmp_eq_u32_e32 vcc, 0, v1
	s_and_saveexec_b64 s[6:7], vcc
	s_cbranch_execz .LBB0_468
	s_bcnt1_i32_b64 s4, s[4:5]
	v_mov_b32_e32 v2, s4
	v_readlane_b32 s4, v245, 15
	v_readlane_b32 s5, v245, 16
	s_nop 4
	global_atomic_add v2, v169, v2, s[4:5] sc0

; __device__ __forceinline__ unsigned xb_ld(unsigned* p)              { return __hip_atomic_load(p, __ATOMIC_RELAXED, __HIP_MEMORY_SCOPE_AGENT); }
; __device__ __forceinline__ unsigned xb_add(unsigned* p, unsigned v) { return __hip_atomic_fetch_add(p, v, __ATOMIC_RELAXED, __HIP_MEMORY_SCOPE_AGENT); }
; #define XB_SPIN(cond, bar) do { unsigned _sp = 0; while (cond) { \
;     if ((++_sp & 255u) == 0u) { if (xb_ld(&(bar)[XB_TMO])) break; if (_sp > XB_SPIN_CAP) { atomicAdd(&(bar)[XB_TMO], 1u); break; } } } } while (0)
; __device__ __forceinline__ void xcd_barrier(const XcdBarrier& b) {
;     ...
;             if (og + 1u == (tg + 1u) * nx) xb_add(&bar[XB_TOPGEN], 1u);
;             else XB_SPIN(xb_ld(&bar[XB_TOPGEN]) == tg, bar);
;             __builtin_amdgcn_fence(__ATOMIC_ACQUIRE, "agent");
;             xb_add(&bar[XB_XGEN(b.x)], 1u);
;             asm volatile("s_waitcnt vmcnt(0)" ::: "memory");
.LBB0_482:
	s_or_b64 exec, exec, s[4:5]
	s_mov_b64 s[4:5], exec
	v_mbcnt_lo_u32_b32 v0, s4, 0
	v_mbcnt_hi_u32_b32 v0, s5, v0
	v_cmp_eq_u32_e32 vcc, 0, v0
	s_waitcnt vmcnt(0)
	s_and_saveexec_b64 s[6:7], vcc
	s_cbranch_execz .LBB0_484
	s_bcnt1_i32_b64 s4, s[4:5]
	v_mov_b32_e32 v0, s4
	v_readlane_b32 s4, v245, 13
	v_readlane_b32 s5, v245, 14
	s_nop 4
	global_atomic_add v169, v0, s[4:5]

; __device__ __forceinline__ unsigned xb_ld(unsigned* p)              { return __hip_atomic_load(p, __ATOMIC_RELAXED, __HIP_MEMORY_SCOPE_AGENT); }
; __device__ __forceinline__ unsigned xb_add(unsigned* p, unsigned v) { return __hip_atomic_fetch_add(p, v, __ATOMIC_RELAXED, __HIP_MEMORY_SCOPE_AGENT); }
; #define XB_SPIN(cond, bar) do { unsigned _sp = 0; while (cond) { \
;     if ((++_sp & 255u) == 0u) { if (xb_ld(&(bar)[XB_TMO])) break; if (_sp > XB_SPIN_CAP) { atomicAdd(&(bar)[XB_TMO], 1u); break; } } } } while (0)
; __device__ __forceinline__ void xcd_barrier(const XcdBarrier& b) {
;     ...
;         const unsigned old = xb_add(&bar[XB_XSUB(b.x)], 1u);
;         const unsigned gen = old / nloc;
;         if (old + 1u == (gen + 1u) * nloc) {
;             __builtin_amdgcn_fence(__ATOMIC_RELEASE, "agent");
;             asm volatile("s_waitcnt vmcnt(0)" ::: "memory");
;             const unsigned og = xb_add(&bar[XB_TOP], 1u);
;             const unsigned tg = og / nx;
;             if (og + 1u == (tg + 1u) * nx) xb_add(&bar[XB_TOPGEN], 1u);
;             else XB_SPIN(xb_ld(&bar[XB_TOPGEN]) == tg, bar);
;             __builtin_amdgcn_fence(__ATOMIC_ACQUIRE, "agent");
;             xb_add(&bar[XB_XGEN(b.x)], 1u);
;             asm volatile("s_waitcnt vmcnt(0)" ::: "memory");
;         } else {
;             XB_SPIN(xb_ld(&bar[XB_XGEN(b.x)]) == gen, bar);
.LBB0_741:
	s_or_b64 exec, exec, s[2:3]
	v_cvt_f32_u32_e32 v4, v2
	s_waitcnt vmcnt(0)
	v_readfirstlane_b32 s2, v3
	v_sub_u32_e32 v3, 0, v2
	v_rcp_iflag_f32_e32 v4, v4
	v_add_u32_e32 v5, s2, v1
	v_mul_f32_e32 v4, 0x4f7ffffe, v4
	v_cvt_u32_f32_e32 v4, v4
	v_mul_lo_u32 v1, v3, v4
	v_mul_hi_u32 v1, v4, v1
	v_add_u32_e32 v1, v4, v1
	v_mul_hi_u32 v1, v5, v1
	v_mul_lo_u32 v3, v1, v2
	v_sub_u32_e32 v3, v5, v3
	v_add_u32_e32 v4, 1, v1
	v_cmp_ge_u32_e32 vcc, v3, v2
	s_nop 1
	v_cndmask_b32_e32 v1, v1, v4, vcc
	v_sub_u32_e32 v4, v3, v2
	v_cndmask_b32_e32 v3, v3, v4, vcc
	v_add_u32_e32 v4, 1, v1
	v_cmp_ge_u32_e32 vcc, v3, v2
	v_add_u32_e32 v3, 1, v5
	s_nop 0
	v_cndmask_b32_e32 v1, v1, v4, vcc
	v_mul_lo_u32 v4, v2, v1
	v_add_u32_e32 v2, v4, v2
	v_cmp_ne_u32_e32 vcc, v3, v2
	s_and_saveexec_b64 s[2:3], vcc
	s_xor_b64 s[2:3], exec, s[2:3]
	s_cbranch_execz .LBB0_755
	buffer_inv sc1
	v_readlane_b32 s4, v245, 13
	v_readlane_b32 s5, v245, 14
	s_waitcnt lgkmcnt(0)
	s_nop 3
	global_load_dword v0, v169, s[4:5] sc1
	s_waitcnt vmcnt(0)
	v_cmp_eq_u32_e32 vcc, v0, v1
	s_and_saveexec_b64 s[4:5], vcc
	s_cbranch_execz .LBB0_754
	s_mov_b32 s10, 1
	s_mov_b64 s[6:7], 0
	s_branch .LBB0_745

; __device__ __forceinline__ unsigned xb_ld(unsigned* p)              { return __hip_atomic_load(p, __ATOMIC_RELAXED, __HIP_MEMORY_SCOPE_AGENT); }
; __device__ __forceinline__ unsigned xb_add(unsigned* p, unsigned v) { return __hip_atomic_fetch_add(p, v, __ATOMIC_RELAXED, __HIP_MEMORY_SCOPE_AGENT); }
; #define XB_SPIN(cond, bar) do { unsigned _sp = 0; while (cond) { \
;     if ((++_sp & 255u) == 0u) { if (xb_ld(&(bar)[XB_TMO])) break; if (_sp > XB_SPIN_CAP) { atomicAdd(&(bar)[XB_TMO], 1u); break; } } } } while (0)
; __device__ __forceinline__ void xcd_barrier(const XcdBarrier& b) {
;     ...
;             __builtin_amdgcn_fence(__ATOMIC_RELEASE, "agent");
;             asm volatile("s_waitcnt vmcnt(0)" ::: "memory");
;             const unsigned og = xb_add(&bar[XB_TOP], 1u);
;             const unsigned tg = og / nx;
;             if (og + 1u == (tg + 1u) * nx) xb_add(&bar[XB_TOPGEN], 1u);
;             else XB_SPIN(xb_ld(&bar[XB_TOPGEN]) == tg, bar);
;             __builtin_amdgcn_fence(__ATOMIC_ACQUIRE, "agent");
;             xb_add(&bar[XB_XGEN(b.x)], 1u);
;             asm volatile("s_waitcnt vmcnt(0)" ::: "memory");
;         } else {
;             XB_SPIN(xb_ld(&bar[XB_XGEN(b.x)]) == gen, bar);
;             __builtin_amdgcn_fence(__ATOMIC_ACQUIRE, "agent");
;             asm volatile("s_waitcnt vmcnt(0)" ::: "memory");
.LBB0_754:
	s_or_b64 exec, exec, s[4:5]
	s_waitcnt vmcnt(0)
	s_waitcnt vmcnt(0)
.LBB0_755:
	s_andn2_saveexec_b64 s[2:3], s[2:3]
	s_cbranch_execz .LBB0_775
	s_mov_b64 s[2:3], exec
	buffer_wbl2 sc1
	s_waitcnt lgkmcnt(0)
	s_waitcnt vmcnt(0)
	buffer_inv sc1
	v_mbcnt_lo_u32_b32 v1, s2, 0
	v_mbcnt_hi_u32_b32 v1, s3, v1
	v_cmp_eq_u32_e32 vcc, 0, v1
	s_and_saveexec_b64 s[4:5], vcc
	s_cbranch_execz .LBB0_758
	s_bcnt1_i32_b64 s2, s[2:3]
	v_mov_b32_e32 v2, s2
	v_readlane_b32 s2, v245, 15
	v_readlane_b32 s3, v245, 16
	s_nop 4
	global_atomic_add v2, v169, v2, s[2:3] sc0

; __device__ __forceinline__ unsigned xb_ld(unsigned* p)              { return __hip_atomic_load(p, __ATOMIC_RELAXED, __HIP_MEMORY_SCOPE_AGENT); }
; __device__ __forceinline__ unsigned xb_add(unsigned* p, unsigned v) { return __hip_atomic_fetch_add(p, v, __ATOMIC_RELAXED, __HIP_MEMORY_SCOPE_AGENT); }
; #define XB_SPIN(cond, bar) do { unsigned _sp = 0; while (cond) { \
;     if ((++_sp & 255u) == 0u) { if (xb_ld(&(bar)[XB_TMO])) break; if (_sp > XB_SPIN_CAP) { atomicAdd(&(bar)[XB_TMO], 1u); break; } } } } while (0)
; __device__ __forceinline__ void xcd_barrier(const XcdBarrier& b) {
;     ...
;             if (og + 1u == (tg + 1u) * nx) xb_add(&bar[XB_TOPGEN], 1u);
;             else XB_SPIN(xb_ld(&bar[XB_TOPGEN]) == tg, bar);
;             __builtin_amdgcn_fence(__ATOMIC_ACQUIRE, "agent");
;             xb_add(&bar[XB_XGEN(b.x)], 1u);
;             asm volatile("s_waitcnt vmcnt(0)" ::: "memory");
.LBB0_772:
	s_or_b64 exec, exec, s[2:3]
	s_mov_b64 s[2:3], exec
	v_mbcnt_lo_u32_b32 v0, s2, 0
	v_mbcnt_hi_u32_b32 v0, s3, v0
	v_cmp_eq_u32_e32 vcc, 0, v0
	s_waitcnt vmcnt(0)
	s_and_saveexec_b64 s[4:5], vcc
	s_cbranch_execz .LBB0_774
	s_bcnt1_i32_b64 s2, s[2:3]
	v_mov_b32_e32 v0, s2
	v_readlane_b32 s2, v245, 13
	v_readlane_b32 s3, v245, 14
	s_nop 4
	global_atomic_add v169, v0, s[2:3]

; #define LAS __attribute__((address_space(3)))
;     __device__ __forceinline__ void operator()(const f32x4 (&acc)[2][2][4][2], const pg8::Unit& u, int wr, int wc, int fr, int fq) const {
;     ...
;         const int row0 = u.pm * 256 + wr * 64 + fr;
;         float rs[2][4];
; #pragma unroll
;         for (int ai = 0; ai < 2; ++ai)
; #pragma unroll
;             for (int m = 0; m < 4; ++m) rs[ai][m] = rsqrtf(SS[row0 + ai * 128 + m * 16] * (1.f / DM) + EPS);
;         if (!RUN_FIX) {
;         if (fr >= 14) {
; #pragma unroll
;             for (int ai = 0; ai < 2; ++ai)
; #pragma unroll
;                 for (int n = 0; n < 2; ++n) *(LAS f32x4*)(halo + ((2 * ai + wr) * 2 + (fr - 14)) * 128 + lc + 4 * n) = acc[ai][0][3][n] * rs[ai][3];
;         }
;         asm volatile("s_waitcnt lgkmcnt(0)" ::: "memory"); __builtin_amdgcn_s_barrier(); asm volatile("" ::: "memory");
;         }
;         u32x2 hkeep[2][4];
; #pragma unroll
;         for (int n = 0; n < 2; ++n) { const int cn = col + 4 * n;
;             const f32x4 w0 = *(const f32x4*)(cw + cn), w1 = *(const f32x4*)(cw + DFF + cn), w2 = *(const f32x4*)(cw + 2 * DFF + cn), bb = *(const f32x4*)(cb + cn);
.LBB0_789:
	s_mov_b32 s6, s81
	v_mov_b32_e32 v230, v225
	s_mov_b32 s10, s74
	v_mov_b32_e32 v96, v226
	s_lshl_b32 s6, s6, 5
	v_lshl_add_u32 v168, v96, 3, s6
	v_lshl_add_u32 v186, s42, 7, v168
	s_cmp_lg_u32 s66, 32
	v_lshl_add_u32 v229, s10, 6, v230
	s_mov_b64 s[6:7], -1
	s_cbranch_scc0 .LBB0_815
	v_lshl_add_u32 v190, s66, 8, v229
	v_ashrrev_i32_e32 v191, 31, v190
	v_lshl_add_u64 v[104:105], v[190:191], 2, s[62:63]
	global_load_dword v98, v[104:105], off
	global_load_dword v97, v[104:105], off offset:64
	global_load_dword v96, v[104:105], off offset:128
	global_load_dword v99, v[104:105], off offset:192
	global_load_dword v193, v[104:105], off offset:512
	global_load_dword v191, v[104:105], off offset:576
	global_load_dword v189, v[104:105], off offset:640
	global_load_dword v255, v[104:105], off offset:704
	v_lshlrev_b32_e32 v254, 2, v186
	global_load_dwordx4 v[156:159], v254, s[26:27]
	global_load_dwordx4 v[152:155], v254, s[34:35]
	global_load_dwordx4 v[148:151], v254, s[22:23]
	global_load_dwordx4 v[144:147], v254, s[38:39]
	v_cmp_lt_i32_e64 s[40:41], 13, v230
	s_waitcnt vmcnt(4)
	v_fmamk_f32 v99, v99, 0x3a000000, v212
	v_cmp_gt_f32_e32 vcc, s14, v99
	v_mul_f32_e32 v106, 0x4b800000, v99
	s_nop 0
	v_cndmask_b32_e32 v99, v99, v106, vcc
	v_rsq_f32_e32 v99, v99
	s_nop 0
	v_mul_f32_e32 v106, 0x45800000, v99
	v_cndmask_b32_e32 v192, v99, v106, vcc
	v_fmamk_f32 v255, v255, 0x3a000000, v212
	v_cmp_gt_f32_e32 vcc, s14, v255
	v_mul_f32_e32 v104, 0x4b800000, v255
	s_nop 0
	v_cndmask_b32_e32 v255, v255, v104, vcc
	v_rsq_f32_e32 v255, v255
	s_nop 0
	v_mul_f32_e32 v104, 0x45800000, v255
	v_cndmask_b32_e32 v188, v255, v104, vcc
	s_and_saveexec_b64 s[6:7], s[40:41]
	s_cbranch_execz .LBB0_792
	s_lshl_b32 s25, s10, 10
	s_add_i32 s25, s25, 0
	v_lshlrev_b32_e32 v99, 9, v230
	s_add_i32 s25, s25, 0x20800
	v_lshlrev_b32_e32 v136, 2, v168
	v_add3_u32 v99, s25, v99, v136
	v_pk_mul_f32 v[106:107], v[38:39], v[192:193] op_sel_hi:[1,0]
	v_pk_mul_f32 v[104:105], v[36:37], v[192:193] op_sel_hi:[1,0]
	v_add_u32_e32 v136, 0xffffe400, v99
	ds_write_b128 v136, v[104:107]
	v_pk_mul_f32 v[106:107], v[6:7], v[192:193] op_sel_hi:[1,0]
	v_pk_mul_f32 v[104:105], v[4:5], v[192:193] op_sel_hi:[1,0]
	v_add_u32_e32 v136, 0xffffe410, v99
	ds_write_b128 v136, v[104:107]
	v_pk_mul_f32 v[106:107], v[110:111], v[188:189] op_sel_hi:[1,0]
	v_pk_mul_f32 v[104:105], v[108:109], v[188:189] op_sel_hi:[1,0]
	v_add_u32_e32 v136, 0xffffec00, v99
	ds_write_b128 v136, v[104:107]
	v_pk_mul_f32 v[106:107], v[70:71], v[188:189] op_sel_hi:[1,0]
	v_pk_mul_f32 v[104:105], v[68:69], v[188:189] op_sel_hi:[1,0]
	v_add_u32_e32 v99, 0xffffec10, v99
	ds_write_b128 v99, v[104:107]
.LBB0_792:
	s_or_b64 exec, exec, s[6:7]
	v_ashrrev_i32_e32 v187, 31, v186
	v_lshlrev_b64 v[104:105], 2, v[186:187]
	s_waitcnt lgkmcnt(0)
	s_barrier
	v_lshl_add_u64 v[208:209], s[26:27], 0, v[104:105]
	v_lshl_add_u64 v[106:107], s[34:35], 0, v[104:105]
	v_lshl_add_u64 v[206:207], s[38:39], 0, v[104:105]
	v_lshl_add_u64 v[136:137], s[22:23], 0, v[104:105]
	s_cmp_gt_i32 s10, 0
	v_mov_b32_e32 v104, 0
	s_cselect_b64 s[6:7], -1, 0
	s_cmp_lt_i32 s10, 1
	v_mov_b32_e32 v136, 0
	v_mov_b32_e32 v137, 0
	v_mov_b32_e32 v138, 0
	v_mov_b32_e32 v139, 0
	s_cbranch_scc1 .LBB0_794
	s_lshl_b32 s25, s10, 10
	s_add_i32 s25, s25, 0
	s_add_i32 s25, s25, 0x20800
	v_lshl_add_u32 v99, v168, 2, s25
	v_add_u32_e32 v99, 0xfffffc00, v99
	ds_read_b128 v[136:139], v99

; __device__ __forceinline__ unsigned xb_add(unsigned* p, unsigned v) { return __hip_atomic_fetch_add(p, v, __ATOMIC_RELAXED, __HIP_MEMORY_SCOPE_AGENT); }
; __device__ __forceinline__ void xcd_barrier(const XcdBarrier& b) {
;     ...
;             __builtin_amdgcn_fence(__ATOMIC_RELEASE, "agent");
;             asm volatile("s_waitcnt vmcnt(0)" ::: "memory");
;             const unsigned og = xb_add(&bar[XB_TOP], 1u);
.LBB0_852:
	s_andn2_saveexec_b64 s[2:3], s[2:3]
	s_cbranch_execz .LBB0_872
	s_mov_b64 s[4:5], exec
	buffer_wbl2 sc1
	s_waitcnt lgkmcnt(0)
	s_waitcnt vmcnt(0)
	buffer_inv sc1
	v_mbcnt_lo_u32_b32 v1, s4, 0
	v_mbcnt_hi_u32_b32 v1, s5, v1
	v_cmp_eq_u32_e32 vcc, 0, v1
	s_and_saveexec_b64 s[6:7], vcc
	s_cbranch_execz .LBB0_855
	s_bcnt1_i32_b64 s4, s[4:5]
	v_mov_b32_e32 v2, s4
	v_readlane_b32 s4, v245, 15
	v_readlane_b32 s5, v245, 16
	s_nop 4
	global_atomic_add v2, v169, v2, s[4:5] sc0

; __device__ __forceinline__ unsigned xb_ld(unsigned* p)              { return __hip_atomic_load(p, __ATOMIC_RELAXED, __HIP_MEMORY_SCOPE_AGENT); }
; __device__ __forceinline__ unsigned xb_add(unsigned* p, unsigned v) { return __hip_atomic_fetch_add(p, v, __ATOMIC_RELAXED, __HIP_MEMORY_SCOPE_AGENT); }
; #define XB_SPIN(cond, bar) do { unsigned _sp = 0; while (cond) { \
;     if ((++_sp & 255u) == 0u) { if (xb_ld(&(bar)[XB_TMO])) break; if (_sp > XB_SPIN_CAP) { atomicAdd(&(bar)[XB_TMO], 1u); break; } } } } while (0)
; __device__ __forceinline__ void xcd_barrier(const XcdBarrier& b) {
;     ...
;             if (og + 1u == (tg + 1u) * nx) xb_add(&bar[XB_TOPGEN], 1u);
;             else XB_SPIN(xb_ld(&bar[XB_TOPGEN]) == tg, bar);
;             __builtin_amdgcn_fence(__ATOMIC_ACQUIRE, "agent");
;             xb_add(&bar[XB_XGEN(b.x)], 1u);
;             asm volatile("s_waitcnt vmcnt(0)" ::: "memory");
.LBB0_1070:
	s_or_b64 exec, exec, s[2:3]
	s_mov_b64 s[2:3], exec
	v_mbcnt_lo_u32_b32 v0, s2, 0
	v_mbcnt_hi_u32_b32 v0, s3, v0
	v_cmp_eq_u32_e32 vcc, 0, v0
	s_waitcnt vmcnt(0)
	s_and_saveexec_b64 s[4:5], vcc
	s_cbranch_execz .LBB0_238
	s_bcnt1_i32_b64 s2, s[2:3]
	v_mov_b32_e32 v0, s2
	v_readlane_b32 s2, v245, 13
	v_readlane_b32 s3, v245, 14
	s_nop 4
	global_atomic_add v169, v0, s[2:3]
	s_branch .LBB0_238
